# combo8 + GEMM DMA k-loop variant: DMA issued after the first MFMAs of each phase
# baseline (speedup 1.0000x reference)
; #define GLOAD(dst, kt_) _Pragma("unroll") for (int i = 0; i < NCH; ++i) { dst[i] = (i < NCHW) ? ldw(i, tid >> 3, (kt_) * 64 + (tid & 7) * 8) : ldx(i - NCHW, tid >> 3, (kt_) * 64 + (tid & 7) * 8); }
; #define LSTORE(src, base) _Pragma("unroll") for (int i = 0; i < NCH; ++i) { const int c = tid + 256 * i; *(u32x4*)((base) + (c >> 3) * 144 + (c & 7) * 16) = src[i]; }
; template <int WGN, int INS, int IMS, bool DB, class LdW, class LdX>
; DI void gemm_core(f32x16 (&acc)[INS][IMS], const int KT, LdW ldw, LdX ldx, char* lds, const int tid) {
;     ...
;     for (int kt = 0; kt < KT; kt += 2) {
;       if (kt + 2 < KT) { GLOAD(preA, kt + 2) }
;       COMPUTE_PIPE(lds)
;       LSTORE(preB, lds + BUFB)
;       __syncthreads();
;       if (kt + 3 < KT) { GLOAD(preB, kt + 3) }
;       COMPUTE_PIPE(lds + BUFB)
;       if (kt + 2 < KT) { LSTORE(preA, lds) }
;       __syncthreads();
;     }
.Lga_loop:
	s_waitcnt vmcnt(0)
	s_barrier
	ds_read_b128 v[160:163], v206 offset:0
	ds_read_b128 v[236:239], v206 offset:4096
	ds_read_b128 v[128:131], v202 offset:32768
	ds_read_b128 v[144:147], v202 offset:36864
	ds_read_b128 v[164:167], v207 offset:0
	ds_read_b128 v[240:243], v207 offset:4096
	ds_read_b128 v[132:135], v203 offset:32768
	ds_read_b128 v[148:151], v203 offset:36864
	s_waitcnt lgkmcnt(4)
	v_mfma_f32_32x32x16_bf16 v[112:127], v[128:131], v[160:163], v[112:127]
	v_mfma_f32_32x32x16_bf16 v[48:63], v[128:131], v[236:239], v[48:63]
	s_add_u32 s8, s8, 0x80
	s_addc_u32 s9, s9, 0
	s_add_u32 m0, s13, 49152
	s_nop 0
	global_load_lds_dwordx4 v210, s[8:9]
	global_load_lds_dwordx4 v211, s[8:9] offset:1024
	global_load_lds_dwordx4 v212, s[8:9] offset:2048
	global_load_lds_dwordx4 v213, s[8:9] offset:3072
	s_add_u32 s10, s10, 0x80
	s_addc_u32 s11, s11, 0
	s_add_u32 m0, s13, 16384
	s_nop 0
	global_load_lds_dwordx4 v216, s[10:11]
	global_load_lds_dwordx4 v217, s[10:11] offset:1024
	global_load_lds_dwordx4 v218, s[10:11] offset:2048
	global_load_lds_dwordx4 v219, s[10:11] offset:3072
	ds_read_b128 v[168:171], v208 offset:0
	ds_read_b128 v[244:247], v208 offset:4096
	ds_read_b128 v[136:139], v204 offset:32768
	ds_read_b128 v[152:155], v204 offset:36864
	v_mfma_f32_32x32x16_bf16 v[96:111], v[144:147], v[160:163], v[96:111]
	v_mfma_f32_32x32x16_bf16 v[32:47], v[144:147], v[236:239], v[32:47]
	s_waitcnt lgkmcnt(4)
	v_mfma_f32_32x32x16_bf16 v[112:127], v[132:135], v[164:167], v[112:127]
	v_mfma_f32_32x32x16_bf16 v[48:63], v[132:135], v[240:243], v[48:63]
	ds_read_b128 v[172:175], v209 offset:0
	ds_read_b128 v[248:251], v209 offset:4096
	ds_read_b128 v[140:143], v205 offset:32768
	ds_read_b128 v[156:159], v205 offset:36864
	v_mfma_f32_32x32x16_bf16 v[96:111], v[148:151], v[164:167], v[96:111]
	v_mfma_f32_32x32x16_bf16 v[32:47], v[148:151], v[240:243], v[32:47]
	s_waitcnt lgkmcnt(4)
	v_mfma_f32_32x32x16_bf16 v[112:127], v[136:139], v[168:171], v[112:127]
	v_mfma_f32_32x32x16_bf16 v[48:63], v[136:139], v[244:247], v[48:63]
	v_mfma_f32_32x32x16_bf16 v[96:111], v[152:155], v[168:171], v[96:111]
	v_mfma_f32_32x32x16_bf16 v[32:47], v[152:155], v[244:247], v[32:47]
	s_waitcnt lgkmcnt(0)
	v_mfma_f32_32x32x16_bf16 v[112:127], v[140:143], v[172:175], v[112:127]
	v_mfma_f32_32x32x16_bf16 v[48:63], v[140:143], v[248:251], v[48:63]
	v_mfma_f32_32x32x16_bf16 v[96:111], v[156:159], v[172:175], v[96:111]
	v_mfma_f32_32x32x16_bf16 v[32:47], v[156:159], v[248:251], v[32:47]
	s_waitcnt vmcnt(4)
	s_barrier
	ds_read_b128 v[128:131], v202 offset:49152
	ds_read_b128 v[144:147], v202 offset:53248
	ds_read_b128 v[132:135], v203 offset:49152
	ds_read_b128 v[148:151], v203 offset:53248
	ds_read_b128 v[136:139], v204 offset:49152
	ds_read_b128 v[152:155], v204 offset:53248
	ds_read_b128 v[140:143], v205 offset:49152
	ds_read_b128 v[156:159], v205 offset:53248
	s_waitcnt lgkmcnt(6)
	v_mfma_f32_32x32x16_bf16 v[80:95], v[128:131], v[160:163], v[80:95]
	v_mfma_f32_32x32x16_bf16 v[16:31], v[128:131], v[236:239], v[16:31]
	v_mfma_f32_32x32x16_bf16 v[64:79], v[144:147], v[160:163], v[64:79]
	v_mfma_f32_32x32x16_bf16 v[0:15], v[144:147], v[236:239], v[0:15]
	s_add_u32 s6, s6, 0x80
	s_addc_u32 s7, s7, 0
	s_add_u32 m0, s13, 32768
	s_nop 0
	global_load_lds_dwordx4 v210, s[6:7]
	global_load_lds_dwordx4 v211, s[6:7] offset:1024
	global_load_lds_dwordx4 v212, s[6:7] offset:2048
	global_load_lds_dwordx4 v213, s[6:7] offset:3072
	s_waitcnt lgkmcnt(4)
	v_mfma_f32_32x32x16_bf16 v[80:95], v[132:135], v[164:167], v[80:95]
	v_mfma_f32_32x32x16_bf16 v[16:31], v[132:135], v[240:243], v[16:31]
	v_mfma_f32_32x32x16_bf16 v[64:79], v[148:151], v[164:167], v[64:79]
	v_mfma_f32_32x32x16_bf16 v[0:15], v[148:151], v[240:243], v[0:15]
	s_waitcnt lgkmcnt(2)
	v_mfma_f32_32x32x16_bf16 v[80:95], v[136:139], v[168:171], v[80:95]
	v_mfma_f32_32x32x16_bf16 v[16:31], v[136:139], v[244:247], v[16:31]
	v_mfma_f32_32x32x16_bf16 v[64:79], v[152:155], v[168:171], v[64:79]
	v_mfma_f32_32x32x16_bf16 v[0:15], v[152:155], v[244:247], v[0:15]
	s_waitcnt lgkmcnt(0)
	v_mfma_f32_32x32x16_bf16 v[80:95], v[140:143], v[172:175], v[80:95]
	v_mfma_f32_32x32x16_bf16 v[16:31], v[140:143], v[248:251], v[16:31]
	v_mfma_f32_32x32x16_bf16 v[64:79], v[156:159], v[172:175], v[64:79]
	v_mfma_f32_32x32x16_bf16 v[0:15], v[156:159], v[248:251], v[0:15]
	s_waitcnt vmcnt(0)
	s_barrier
	ds_read_b128 v[160:163], v206 offset:16384
	ds_read_b128 v[236:239], v206 offset:20480
	ds_read_b128 v[128:131], v202 offset:32768
	ds_read_b128 v[144:147], v202 offset:36864
	ds_read_b128 v[164:167], v207 offset:16384
	ds_read_b128 v[240:243], v207 offset:20480
	ds_read_b128 v[132:135], v203 offset:32768
	ds_read_b128 v[148:151], v203 offset:36864
	s_waitcnt lgkmcnt(4)
	v_mfma_f32_32x32x16_bf16 v[112:127], v[128:131], v[160:163], v[112:127]
	v_mfma_f32_32x32x16_bf16 v[48:63], v[128:131], v[236:239], v[48:63]
	s_add_u32 s8, s8, 0x80
	s_addc_u32 s9, s9, 0
	s_add_u32 m0, s13, 49152
	s_nop 0
	global_load_lds_dwordx4 v210, s[8:9]
	global_load_lds_dwordx4 v211, s[8:9] offset:1024
	global_load_lds_dwordx4 v212, s[8:9] offset:2048
	global_load_lds_dwordx4 v213, s[8:9] offset:3072
	s_cmp_eq_u32 s12, 7
	s_cbranch_scc1 .Lga_skipx
	s_add_u32 s10, s10, 0x80
	s_addc_u32 s11, s11, 0
	s_add_u32 m0, s13, 0
	s_nop 0
	global_load_lds_dwordx4 v216, s[10:11]
	global_load_lds_dwordx4 v217, s[10:11] offset:1024
	global_load_lds_dwordx4 v218, s[10:11] offset:2048
	global_load_lds_dwordx4 v219, s[10:11] offset:3072
; #define GLOAD(dst, kt_) _Pragma("unroll") for (int i = 0; i < NCH; ++i) { dst[i] = (i < NCHW) ? ldw(i, tid >> 3, (kt_) * 64 + (tid & 7) * 8) : ldx(i - NCHW, tid >> 3, (kt_) * 64 + (tid & 7) * 8); }
; #define LSTORE(src, base) _Pragma("unroll") for (int i = 0; i < NCH; ++i) { const int c = tid + 256 * i; *(u32x4*)((base) + (c >> 3) * 144 + (c & 7) * 16) = src[i]; }
; template <int WGN, int INS, int IMS, bool DB, class LdW, class LdX>
; DI void gemm_core(f32x16 (&acc)[INS][IMS], const int KT, LdW ldw, LdX ldx, char* lds, const int tid) {
;     ...
;     for (int kt = 0; kt < KT; kt += 2) {
;       if (kt + 2 < KT) { GLOAD(preA, kt + 2) }
;       COMPUTE_PIPE(lds)
;       LSTORE(preB, lds + BUFB)
;       __syncthreads();
;       if (kt + 3 < KT) { GLOAD(preB, kt + 3) }
;       COMPUTE_PIPE(lds + BUFB)
;       if (kt + 2 < KT) { LSTORE(preA, lds) }
;       __syncthreads();
;     }
; template <int NTW>
; DI void inproj_tile(const Params& p, int l, int mt, int ntile, char* lds) {
;     ...
;   const int lane = tid & 63, wid = tid >> 6, l31 = lane & 31, hi = lane >> 5, wn = wid >> 1, wm = wid & 1;
;   const float* rn = (const float*)(ws_ + OFF_RN);
;   u16* proj = (u16*)(ws_ + OFF_PROJ);
;   constexpr int NCOLS = 64 * NTW, RS = NCOLS * 2 + 16;
;   __syncthreads();
; #pragma unroll
;   for (int im = 0; im < 2; ++im) {
;     const int tl = wm * 64 + im * 32 + l31;
;     const float r = rn[(size_t)mt * 128 + tl];
.Lga_skipx:
	ds_read_b128 v[168:171], v208 offset:16384
	ds_read_b128 v[244:247], v208 offset:20480
	ds_read_b128 v[136:139], v204 offset:32768
	ds_read_b128 v[152:155], v204 offset:36864
	v_mfma_f32_32x32x16_bf16 v[96:111], v[144:147], v[160:163], v[96:111]
	v_mfma_f32_32x32x16_bf16 v[32:47], v[144:147], v[236:239], v[32:47]
	s_waitcnt lgkmcnt(4)
	v_mfma_f32_32x32x16_bf16 v[112:127], v[132:135], v[164:167], v[112:127]
	v_mfma_f32_32x32x16_bf16 v[48:63], v[132:135], v[240:243], v[48:63]
	ds_read_b128 v[172:175], v209 offset:16384
	ds_read_b128 v[248:251], v209 offset:20480
	ds_read_b128 v[140:143], v205 offset:32768
	ds_read_b128 v[156:159], v205 offset:36864
	v_mfma_f32_32x32x16_bf16 v[96:111], v[148:151], v[164:167], v[96:111]
	v_mfma_f32_32x32x16_bf16 v[32:47], v[148:151], v[240:243], v[32:47]
	s_waitcnt lgkmcnt(4)
	v_mfma_f32_32x32x16_bf16 v[112:127], v[136:139], v[168:171], v[112:127]
	v_mfma_f32_32x32x16_bf16 v[48:63], v[136:139], v[244:247], v[48:63]
	v_mfma_f32_32x32x16_bf16 v[96:111], v[152:155], v[168:171], v[96:111]
	v_mfma_f32_32x32x16_bf16 v[32:47], v[152:155], v[244:247], v[32:47]
	s_waitcnt lgkmcnt(0)
	v_mfma_f32_32x32x16_bf16 v[112:127], v[140:143], v[172:175], v[112:127]
	v_mfma_f32_32x32x16_bf16 v[48:63], v[140:143], v[248:251], v[48:63]
	v_mfma_f32_32x32x16_bf16 v[96:111], v[156:159], v[172:175], v[96:111]
	v_mfma_f32_32x32x16_bf16 v[32:47], v[156:159], v[248:251], v[32:47]
	s_cmp_eq_u32 s12, 7
	s_cbranch_scc1 .Lga_lastp1
	s_waitcnt vmcnt(4)
	s_barrier
	ds_read_b128 v[128:131], v202 offset:49152
	ds_read_b128 v[144:147], v202 offset:53248
	ds_read_b128 v[132:135], v203 offset:49152
	ds_read_b128 v[148:151], v203 offset:53248
	ds_read_b128 v[136:139], v204 offset:49152
	ds_read_b128 v[152:155], v204 offset:53248
	ds_read_b128 v[140:143], v205 offset:49152
	ds_read_b128 v[156:159], v205 offset:53248
	s_waitcnt lgkmcnt(6)
	v_mfma_f32_32x32x16_bf16 v[80:95], v[128:131], v[160:163], v[80:95]
	v_mfma_f32_32x32x16_bf16 v[16:31], v[128:131], v[236:239], v[16:31]
	v_mfma_f32_32x32x16_bf16 v[64:79], v[144:147], v[160:163], v[64:79]
	v_mfma_f32_32x32x16_bf16 v[0:15], v[144:147], v[236:239], v[0:15]
	s_add_u32 s6, s6, 0x80
	s_addc_u32 s7, s7, 0
	s_add_u32 m0, s13, 32768
	s_nop 0
	global_load_lds_dwordx4 v210, s[6:7]
	global_load_lds_dwordx4 v211, s[6:7] offset:1024
	global_load_lds_dwordx4 v212, s[6:7] offset:2048
	global_load_lds_dwordx4 v213, s[6:7] offset:3072
	s_branch .Lga_p1c
.Lga_lastp1:
	s_waitcnt vmcnt(0)
	s_barrier
	ds_read_b128 v[128:131], v202 offset:49152
	ds_read_b128 v[144:147], v202 offset:53248
	ds_read_b128 v[132:135], v203 offset:49152
	ds_read_b128 v[148:151], v203 offset:53248
	ds_read_b128 v[136:139], v204 offset:49152
	ds_read_b128 v[152:155], v204 offset:53248
	ds_read_b128 v[140:143], v205 offset:49152
	ds_read_b128 v[156:159], v205 offset:53248
	s_waitcnt lgkmcnt(6)
	v_mfma_f32_32x32x16_bf16 v[80:95], v[128:131], v[160:163], v[80:95]
	v_mfma_f32_32x32x16_bf16 v[16:31], v[128:131], v[236:239], v[16:31]
	v_mfma_f32_32x32x16_bf16 v[64:79], v[144:147], v[160:163], v[64:79]
	v_mfma_f32_32x32x16_bf16 v[0:15], v[144:147], v[236:239], v[0:15]
.Lga_p1c:
	s_waitcnt lgkmcnt(4)
	v_mfma_f32_32x32x16_bf16 v[80:95], v[132:135], v[164:167], v[80:95]
	v_mfma_f32_32x32x16_bf16 v[16:31], v[132:135], v[240:243], v[16:31]
	v_mfma_f32_32x32x16_bf16 v[64:79], v[148:151], v[164:167], v[64:79]
	v_mfma_f32_32x32x16_bf16 v[0:15], v[148:151], v[240:243], v[0:15]
	s_waitcnt lgkmcnt(2)
	v_mfma_f32_32x32x16_bf16 v[80:95], v[136:139], v[168:171], v[80:95]
	v_mfma_f32_32x32x16_bf16 v[16:31], v[136:139], v[244:247], v[16:31]
	v_mfma_f32_32x32x16_bf16 v[64:79], v[152:155], v[168:171], v[64:79]
	v_mfma_f32_32x32x16_bf16 v[0:15], v[152:155], v[244:247], v[0:15]
	s_waitcnt lgkmcnt(0)
	v_mfma_f32_32x32x16_bf16 v[80:95], v[140:143], v[172:175], v[80:95]
	v_mfma_f32_32x32x16_bf16 v[16:31], v[140:143], v[248:251], v[16:31]
	v_mfma_f32_32x32x16_bf16 v[64:79], v[156:159], v[172:175], v[64:79]
	v_mfma_f32_32x32x16_bf16 v[0:15], v[156:159], v[248:251], v[0:15]
	s_add_i32 s12, s12, 1
	s_cmp_lg_u32 s12, 8
	s_cbranch_scc1 .Lga_loop
	s_nop 15
	s_barrier
	s_add_u32 s2, s27, 0x4a40000
	s_addc_u32 s3, s28, 0
	s_lshl_b64 s[0:1], s[0:1], 1
	s_add_u32 s0, s27, s0
	s_addc_u32 s1, s28, s1
	s_add_u32 s0, s0, 0x4a50000
	s_addc_u32 s1, s1, 0
	v_and_b32_e32 v128, 0x7fffff80, v181
	v_and_or_b32 v129, v185, 4, v128
	v_or_b32_e32 v128, s80, v183
	v_lshlrev_b32_e32 v132, 2, v128
	v_mov_b32_e32 v128, v252
	s_waitcnt vmcnt(0)
; template <int NTW>
; DI void inproj_tile(const Params& p, int l, int mt, int ntile, char* lds) {
;     ...
; #pragma unroll
;   for (int im = 0; im < 2; ++im) {
;     const int tl = wm * 64 + im * 32 + l31;
;     const float r = rn[(size_t)mt * 128 + tl];
; #pragma unroll
;     for (int in = 0; in < NTW; ++in)
; #pragma unroll
;       for (int g = 0; g < 4; ++g) {
;         const int n = wn * 32 * NTW + in * 32 + 8 * g + 4 * hi;
;         u32x2 o; o[0] = pk2(acc[in][im][4 * g] * r, acc[in][im][4 * g + 1] * r); o[1] = pk2(acc[in][im][4 * g + 2] * r, acc[in][im][4 * g + 3] * r);
;         *(u32x2*)(lds + tl * RS + n * 2) = o;
;       }
;   }
	s_nop 2
	v_mul_f32_e64 v112, v112, v128
	v_mul_f32_e64 v113, v113, v128
	v_cvt_pk_bf16_f32 v130, v112, v113
	v_mul_f32_e64 v112, v114, v128
	v_mul_f32_e64 v113, v115, v128
	v_mul_f32_e64 v96, v96, v128
	v_mul_f32_e64 v97, v97, v128
	v_cvt_pk_bf16_f32 v131, v112, v113
	v_lshlrev_b32_e32 v112, 1, v129
	v_mad_u32_u24 v112, v183, s73, v112
	v_pk_mul_f32 v[98:99], v[98:99], v[128:129] op_sel_hi:[1,0]
	s_nop 2
	v_pk_mul_f32 v[64:65], v[64:65], v[128:129] op_sel_hi:[1,0]
	v_pk_mul_f32 v[66:67], v[66:67], v[128:129] op_sel_hi:[1,0]
	v_cvt_pk_bf16_f32 v64, v64, v65
	v_cvt_pk_bf16_f32 v65, v66, v67
	v_pk_mul_f32 v[66:67], v[68:69], v[128:129] op_sel_hi:[1,0]
	v_pk_mul_f32 v[68:69], v[70:71], v[128:129] op_sel_hi:[1,0]
	v_cvt_pk_bf16_f32 v66, v66, v67
	v_cvt_pk_bf16_f32 v67, v68, v69
	ds_write2_b64 v112, v[64:65], v[66:67] offset0:24 offset1:26
	v_pk_mul_f32 v[64:65], v[72:73], v[128:129] op_sel_hi:[1,0]
	v_pk_mul_f32 v[66:67], v[74:75], v[128:129] op_sel_hi:[1,0]
	v_cvt_pk_bf16_f32 v64, v64, v65
	v_cvt_pk_bf16_f32 v65, v66, v67
	v_pk_mul_f32 v[66:67], v[76:77], v[128:129] op_sel_hi:[1,0]
	v_pk_mul_f32 v[68:69], v[78:79], v[128:129] op_sel_hi:[1,0]
	v_cvt_pk_bf16_f32 v66, v66, v67
	v_cvt_pk_bf16_f32 v67, v68, v69
	ds_write2_b64 v112, v[64:65], v[66:67] offset0:28 offset1:30
	v_or_b32_e32 v64, 0x80, v132
	v_mov_b32_e32 v64, v253
	v_mul_f32_e64 v114, v116, v128
	v_mul_f32_e64 v115, v117, v128
	v_mul_f32_e64 v116, v118, v128
	v_mul_f32_e64 v117, v119, v128
	v_cvt_pk_bf16_f32 v96, v96, v97
	v_cvt_pk_bf16_f32 v97, v98, v99
	v_pk_mul_f32 v[98:99], v[100:101], v[128:129] op_sel_hi:[1,0]
	v_pk_mul_f32 v[100:101], v[102:103], v[128:129] op_sel_hi:[1,0]
	v_cvt_pk_bf16_f32 v114, v114, v115
	s_nop 1
	v_mul_f32_e64 v80, v80, v128
	v_mul_f32_e64 v81, v81, v128
	v_mul_f32_e64 v82, v82, v128
	v_mul_f32_e64 v83, v83, v128
	v_cvt_pk_bf16_f32 v80, v80, v81
	v_cvt_pk_bf16_f32 v81, v82, v83
	v_pk_mul_f32 v[82:83], v[84:85], v[128:129] op_sel_hi:[1,0]
	v_pk_mul_f32 v[84:85], v[86:87], v[128:129] op_sel_hi:[1,0]
	v_cvt_pk_bf16_f32 v115, v116, v117
	v_cvt_pk_bf16_f32 v98, v98, v99
	v_cvt_pk_bf16_f32 v99, v100, v101
	v_cvt_pk_bf16_f32 v82, v82, v83
	v_cvt_pk_bf16_f32 v83, v84, v85
	ds_write2_b64 v112, v[130:131], v[114:115] offset1:2
	v_pk_mul_f32 v[114:115], v[120:121], v[128:129] op_sel_hi:[1,0]
	v_pk_mul_f32 v[116:117], v[122:123], v[128:129] op_sel_hi:[1,0]
	ds_write2_b64 v112, v[96:97], v[98:99] offset0:8 offset1:10
	v_pk_mul_f32 v[96:97], v[104:105], v[128:129] op_sel_hi:[1,0]
	v_pk_mul_f32 v[98:99], v[106:107], v[128:129] op_sel_hi:[1,0]
	ds_write2_b64 v112, v[80:81], v[82:83] offset0:16 offset1:18
	v_pk_mul_f32 v[80:81], v[88:89], v[128:129] op_sel_hi:[1,0]
	v_pk_mul_f32 v[82:83], v[90:91], v[128:129] op_sel_hi:[1,0]
	v_cvt_pk_bf16_f32 v114, v114, v115
	v_cvt_pk_bf16_f32 v115, v116, v117
	v_pk_mul_f32 v[116:117], v[124:125], v[128:129] op_sel_hi:[1,0]
	v_pk_mul_f32 v[118:119], v[126:127], v[128:129] op_sel_hi:[1,0]
	v_cvt_pk_bf16_f32 v96, v96, v97
	v_cvt_pk_bf16_f32 v97, v98, v99
	v_pk_mul_f32 v[98:99], v[108:109], v[128:129] op_sel_hi:[1,0]
	v_pk_mul_f32 v[100:101], v[110:111], v[128:129] op_sel_hi:[1,0]
	v_cvt_pk_bf16_f32 v80, v80, v81
	v_cvt_pk_bf16_f32 v81, v82, v83
	v_pk_mul_f32 v[82:83], v[92:93], v[128:129] op_sel_hi:[1,0]
	v_pk_mul_f32 v[84:85], v[94:95], v[128:129] op_sel_hi:[1,0]
	v_cvt_pk_bf16_f32 v116, v116, v117
	v_cvt_pk_bf16_f32 v117, v118, v119
	v_cvt_pk_bf16_f32 v98, v98, v99
	v_cvt_pk_bf16_f32 v99, v100, v101
	v_cvt_pk_bf16_f32 v82, v82, v83
	v_cvt_pk_bf16_f32 v83, v84, v85
	s_mov_b32 s2, 0
	ds_write2_b64 v112, v[114:115], v[116:117] offset0:4 offset1:6
	ds_write2_b64 v112, v[96:97], v[98:99] offset0:12 offset1:14
	ds_write2_b64 v112, v[80:81], v[82:83] offset0:20 offset1:22
	s_waitcnt vmcnt(0)
; template <int NTW>
; DI void inproj_tile(const Params& p, int l, int mt, int ntile, char* lds) {
;     ...
; #pragma unroll
;   for (int im = 0; im < 2; ++im) {
;     const int tl = wm * 64 + im * 32 + l31;
;     const float r = rn[(size_t)mt * 128 + tl];
; #pragma unroll
;     for (int in = 0; in < NTW; ++in)
; #pragma unroll
;       for (int g = 0; g < 4; ++g) {
;         const int n = wn * 32 * NTW + in * 32 + 8 * g + 4 * hi;
;         u32x2 o; o[0] = pk2(acc[in][im][4 * g] * r, acc[in][im][4 * g + 1] * r); o[1] = pk2(acc[in][im][4 * g + 2] * r, acc[in][im][4 * g + 3] * r);
;         *(u32x2*)(lds + tl * RS + n * 2) = o;
;       }
;   }
;   __syncthreads();
	v_pk_mul_f32 v[48:49], v[48:49], v[64:65] op_sel_hi:[1,0]
	v_pk_mul_f32 v[50:51], v[50:51], v[64:65] op_sel_hi:[1,0]
	v_pk_mul_f32 v[32:33], v[32:33], v[64:65] op_sel_hi:[1,0]
	v_pk_mul_f32 v[34:35], v[34:35], v[64:65] op_sel_hi:[1,0]
	v_pk_mul_f32 v[16:17], v[16:17], v[64:65] op_sel_hi:[1,0]
	v_pk_mul_f32 v[18:19], v[18:19], v[64:65] op_sel_hi:[1,0]
	v_pk_mul_f32 v[0:1], v[0:1], v[64:65] op_sel_hi:[1,0]
	v_pk_mul_f32 v[2:3], v[2:3], v[64:65] op_sel_hi:[1,0]
	v_cvt_pk_bf16_f32 v48, v48, v49
	v_cvt_pk_bf16_f32 v49, v50, v51
	v_pk_mul_f32 v[50:51], v[52:53], v[64:65] op_sel_hi:[1,0]
	v_pk_mul_f32 v[52:53], v[54:55], v[64:65] op_sel_hi:[1,0]
	v_cvt_pk_bf16_f32 v32, v32, v33
	v_cvt_pk_bf16_f32 v33, v34, v35
	v_pk_mul_f32 v[34:35], v[36:37], v[64:65] op_sel_hi:[1,0]
	v_pk_mul_f32 v[36:37], v[38:39], v[64:65] op_sel_hi:[1,0]
	v_cvt_pk_bf16_f32 v16, v16, v17
	v_cvt_pk_bf16_f32 v17, v18, v19
	v_pk_mul_f32 v[18:19], v[20:21], v[64:65] op_sel_hi:[1,0]
	v_pk_mul_f32 v[20:21], v[22:23], v[64:65] op_sel_hi:[1,0]
	v_cvt_pk_bf16_f32 v0, v0, v1
	v_cvt_pk_bf16_f32 v1, v2, v3
	v_pk_mul_f32 v[2:3], v[4:5], v[64:65] op_sel_hi:[1,0]
	v_pk_mul_f32 v[4:5], v[6:7], v[64:65] op_sel_hi:[1,0]
	v_cvt_pk_bf16_f32 v50, v50, v51
	v_cvt_pk_bf16_f32 v51, v52, v53
	v_add_u32_e32 v54, 0x4000, v112
	v_cvt_pk_bf16_f32 v34, v34, v35
	v_cvt_pk_bf16_f32 v35, v36, v37
	v_cvt_pk_bf16_f32 v18, v18, v19
	v_cvt_pk_bf16_f32 v19, v20, v21
	v_cvt_pk_bf16_f32 v2, v2, v3
	v_cvt_pk_bf16_f32 v3, v4, v5
	ds_write2_b64 v54, v[48:49], v[50:51] offset0:64 offset1:66
	v_pk_mul_f32 v[48:49], v[56:57], v[64:65] op_sel_hi:[1,0]
	v_pk_mul_f32 v[50:51], v[58:59], v[64:65] op_sel_hi:[1,0]
	ds_write2_b64 v54, v[32:33], v[34:35] offset0:72 offset1:74
	v_pk_mul_f32 v[32:33], v[40:41], v[64:65] op_sel_hi:[1,0]
	v_pk_mul_f32 v[34:35], v[42:43], v[64:65] op_sel_hi:[1,0]
	ds_write2_b64 v54, v[16:17], v[18:19] offset0:80 offset1:82
	v_pk_mul_f32 v[16:17], v[24:25], v[64:65] op_sel_hi:[1,0]
	v_pk_mul_f32 v[18:19], v[26:27], v[64:65] op_sel_hi:[1,0]
	ds_write2_b64 v54, v[0:1], v[2:3] offset0:88 offset1:90
	v_pk_mul_f32 v[0:1], v[8:9], v[64:65] op_sel_hi:[1,0]
	v_pk_mul_f32 v[2:3], v[10:11], v[64:65] op_sel_hi:[1,0]
	v_cvt_pk_bf16_f32 v48, v48, v49
	v_cvt_pk_bf16_f32 v49, v50, v51
	v_pk_mul_f32 v[50:51], v[60:61], v[64:65] op_sel_hi:[1,0]
	v_pk_mul_f32 v[52:53], v[62:63], v[64:65] op_sel_hi:[1,0]
	v_cvt_pk_bf16_f32 v32, v32, v33
	v_cvt_pk_bf16_f32 v33, v34, v35
	v_pk_mul_f32 v[34:35], v[44:45], v[64:65] op_sel_hi:[1,0]
	v_pk_mul_f32 v[36:37], v[46:47], v[64:65] op_sel_hi:[1,0]
	v_cvt_pk_bf16_f32 v16, v16, v17
	v_cvt_pk_bf16_f32 v17, v18, v19
	v_pk_mul_f32 v[18:19], v[28:29], v[64:65] op_sel_hi:[1,0]
	v_pk_mul_f32 v[20:21], v[30:31], v[64:65] op_sel_hi:[1,0]
	v_cvt_pk_bf16_f32 v0, v0, v1
	v_cvt_pk_bf16_f32 v1, v2, v3
	v_pk_mul_f32 v[2:3], v[12:13], v[64:65] op_sel_hi:[1,0]
	v_pk_mul_f32 v[4:5], v[14:15], v[64:65] op_sel_hi:[1,0]
	v_cvt_pk_bf16_f32 v50, v50, v51
	v_cvt_pk_bf16_f32 v51, v52, v53
	v_cvt_pk_bf16_f32 v34, v34, v35
	v_cvt_pk_bf16_f32 v35, v36, v37
	v_cvt_pk_bf16_f32 v18, v18, v19
	v_cvt_pk_bf16_f32 v19, v20, v21
	v_cvt_pk_bf16_f32 v2, v2, v3
	v_cvt_pk_bf16_f32 v3, v4, v5
	ds_write2_b64 v54, v[48:49], v[50:51] offset0:68 offset1:70
	ds_write2_b64 v54, v[32:33], v[34:35] offset0:76 offset1:78
	ds_write2_b64 v54, v[16:17], v[18:19] offset0:84 offset1:86
	ds_write2_b64 v54, v[0:1], v[2:3] offset0:92 offset1:94
	s_waitcnt lgkmcnt(0)
	s_barrier

; #define GLOAD(dst, kt_) _Pragma("unroll") for (int i = 0; i < NCH; ++i) { dst[i] = (i < NCHW) ? ldw(i, tid >> 3, (kt_) * 64 + (tid & 7) * 8) : ldx(i - NCHW, tid >> 3, (kt_) * 64 + (tid & 7) * 8); }
; #define LSTORE(src, base) _Pragma("unroll") for (int i = 0; i < NCH; ++i) { const int c = tid + 256 * i; *(u32x4*)((base) + (c >> 3) * 144 + (c & 7) * 16) = src[i]; }
; template <int WGN, int INS, int IMS, bool DB, class LdW, class LdX>
; DI void gemm_core(f32x16 (&acc)[INS][IMS], const int KT, LdW ldw, LdX ldx, char* lds, const int tid) {
;     ...
;     for (int kt = 0; kt < KT; kt += 2) {
;       if (kt + 2 < KT) { GLOAD(preA, kt + 2) }
;       COMPUTE_PIPE(lds)
;       LSTORE(preB, lds + BUFB)
;       __syncthreads();
;       if (kt + 3 < KT) { GLOAD(preB, kt + 3) }
;       COMPUTE_PIPE(lds + BUFB)
;       if (kt + 2 < KT) { LSTORE(preA, lds) }
;       __syncthreads();
;     }
; template <int NTW>
; DI void inproj_tile(const Params& p, int l, int mt, int ntile, char* lds) {
;     ...
;   __syncthreads();
; #pragma unroll
;   for (int im = 0; im < 2; ++im) {
;     const int tl = wm * 64 + im * 32 + l31;
;     const float r = rn[(size_t)mt * 128 + tl];
; #pragma unroll
;     for (int in = 0; in < NTW; ++in)
; #pragma unroll
;       for (int g = 0; g < 4; ++g) {
;         const int n = wn * 32 * NTW + in * 32 + 8 * g + 4 * hi;
;         u32x2 o; o[0] = pk2(acc[in][im][4 * g] * r, acc[in][im][4 * g + 1] * r); o[1] = pk2(acc[in][im][4 * g + 2] * r, acc[in][im][4 * g + 3] * r);
;         *(u32x2*)(lds + tl * RS + n * 2) = o;
;       }
;   }
.Lgb_p1c:
	s_waitcnt lgkmcnt(4)
	v_mfma_f32_32x32x16_bf16 v[80:95], v[132:135], v[164:167], v[80:95]
	v_mfma_f32_32x32x16_bf16 v[16:31], v[132:135], v[240:243], v[16:31]
	v_mfma_f32_32x32x16_bf16 v[64:79], v[148:151], v[164:167], v[64:79]
	v_mfma_f32_32x32x16_bf16 v[0:15], v[148:151], v[240:243], v[0:15]
	s_waitcnt lgkmcnt(2)
	v_mfma_f32_32x32x16_bf16 v[80:95], v[136:139], v[168:171], v[80:95]
	v_mfma_f32_32x32x16_bf16 v[16:31], v[136:139], v[244:247], v[16:31]
	v_mfma_f32_32x32x16_bf16 v[64:79], v[152:155], v[168:171], v[64:79]
	v_mfma_f32_32x32x16_bf16 v[0:15], v[152:155], v[244:247], v[0:15]
	s_waitcnt lgkmcnt(0)
	v_mfma_f32_32x32x16_bf16 v[80:95], v[140:143], v[172:175], v[80:95]
	v_mfma_f32_32x32x16_bf16 v[16:31], v[140:143], v[248:251], v[16:31]
	v_mfma_f32_32x32x16_bf16 v[64:79], v[156:159], v[172:175], v[64:79]
	v_mfma_f32_32x32x16_bf16 v[0:15], v[156:159], v[248:251], v[0:15]
	s_add_i32 s12, s12, 1
	s_cmp_lg_u32 s12, 8
	s_cbranch_scc1 .Lgb_loop
	s_nop 15
	s_setprio 0
	s_barrier
	s_add_u32 s2, s27, 0x4a40000
	s_addc_u32 s3, s37, 0
	s_lshl_b64 s[0:1], s[0:1], 1
	s_add_u32 s0, s27, s0
	s_addc_u32 s1, s37, s1
	s_add_u32 s0, s0, 0x4a50000
	s_addc_u32 s1, s1, 0
	v_and_b32_e32 v128, 0x7fffff80, v181
	v_and_or_b32 v129, v185, 4, v128
	v_or_b32_e32 v128, s80, v183
	v_lshlrev_b32_e32 v132, 2, v128
	v_mov_b32_e32 v128, v252
	s_waitcnt vmcnt(0)
	s_nop 2
	v_mul_f32_e64 v112, v112, v128
	v_mul_f32_e64 v113, v113, v128
	v_cvt_pk_bf16_f32 v130, v112, v113
	v_mul_f32_e64 v112, v114, v128
	v_mul_f32_e64 v113, v115, v128
	v_mul_f32_e64 v96, v96, v128
	v_mul_f32_e64 v97, v97, v128
	v_cvt_pk_bf16_f32 v131, v112, v113
	v_lshlrev_b32_e32 v112, 1, v129
	v_mad_u32_u24 v112, v183, s73, v112
	v_pk_mul_f32 v[98:99], v[98:99], v[128:129] op_sel_hi:[1,0]
	s_nop 2
	v_pk_mul_f32 v[64:65], v[64:65], v[128:129] op_sel_hi:[1,0]
	v_pk_mul_f32 v[66:67], v[66:67], v[128:129] op_sel_hi:[1,0]
	v_cvt_pk_bf16_f32 v64, v64, v65
	v_cvt_pk_bf16_f32 v65, v66, v67
	v_pk_mul_f32 v[66:67], v[68:69], v[128:129] op_sel_hi:[1,0]
	v_pk_mul_f32 v[68:69], v[70:71], v[128:129] op_sel_hi:[1,0]
	v_cvt_pk_bf16_f32 v66, v66, v67
	v_cvt_pk_bf16_f32 v67, v68, v69
	ds_write2_b64 v112, v[64:65], v[66:67] offset0:24 offset1:26
	v_pk_mul_f32 v[64:65], v[72:73], v[128:129] op_sel_hi:[1,0]
	v_pk_mul_f32 v[66:67], v[74:75], v[128:129] op_sel_hi:[1,0]
	v_cvt_pk_bf16_f32 v64, v64, v65
	v_cvt_pk_bf16_f32 v65, v66, v67
	v_pk_mul_f32 v[66:67], v[76:77], v[128:129] op_sel_hi:[1,0]
	v_pk_mul_f32 v[68:69], v[78:79], v[128:129] op_sel_hi:[1,0]
	v_cvt_pk_bf16_f32 v66, v66, v67
	v_cvt_pk_bf16_f32 v67, v68, v69
	ds_write2_b64 v112, v[64:65], v[66:67] offset0:28 offset1:30
	v_or_b32_e32 v64, 0x80, v132
	v_mov_b32_e32 v64, v253
	v_mul_f32_e64 v114, v116, v128
	v_mul_f32_e64 v115, v117, v128
	v_mul_f32_e64 v116, v118, v128
	v_mul_f32_e64 v117, v119, v128
	v_cvt_pk_bf16_f32 v96, v96, v97
	v_cvt_pk_bf16_f32 v97, v98, v99
	v_pk_mul_f32 v[98:99], v[100:101], v[128:129] op_sel_hi:[1,0]
	v_pk_mul_f32 v[100:101], v[102:103], v[128:129] op_sel_hi:[1,0]
	v_cvt_pk_bf16_f32 v114, v114, v115
	s_nop 1
	v_mul_f32_e64 v80, v80, v128
	v_mul_f32_e64 v81, v81, v128
	v_mul_f32_e64 v82, v82, v128
	v_mul_f32_e64 v83, v83, v128
	v_cvt_pk_bf16_f32 v80, v80, v81
	v_cvt_pk_bf16_f32 v81, v82, v83
	v_pk_mul_f32 v[82:83], v[84:85], v[128:129] op_sel_hi:[1,0]
	v_pk_mul_f32 v[84:85], v[86:87], v[128:129] op_sel_hi:[1,0]
	v_cvt_pk_bf16_f32 v115, v116, v117
	v_cvt_pk_bf16_f32 v98, v98, v99
	v_cvt_pk_bf16_f32 v99, v100, v101
	v_cvt_pk_bf16_f32 v82, v82, v83
	v_cvt_pk_bf16_f32 v83, v84, v85
	ds_write2_b64 v112, v[130:131], v[114:115] offset1:2
	v_pk_mul_f32 v[114:115], v[120:121], v[128:129] op_sel_hi:[1,0]
	v_pk_mul_f32 v[116:117], v[122:123], v[128:129] op_sel_hi:[1,0]
	ds_write2_b64 v112, v[96:97], v[98:99] offset0:8 offset1:10
	v_pk_mul_f32 v[96:97], v[104:105], v[128:129] op_sel_hi:[1,0]
	v_pk_mul_f32 v[98:99], v[106:107], v[128:129] op_sel_hi:[1,0]
	ds_write2_b64 v112, v[80:81], v[82:83] offset0:16 offset1:18
	v_pk_mul_f32 v[80:81], v[88:89], v[128:129] op_sel_hi:[1,0]
	v_pk_mul_f32 v[82:83], v[90:91], v[128:129] op_sel_hi:[1,0]
	v_cvt_pk_bf16_f32 v114, v114, v115
	v_cvt_pk_bf16_f32 v115, v116, v117
	v_pk_mul_f32 v[116:117], v[124:125], v[128:129] op_sel_hi:[1,0]
	v_pk_mul_f32 v[118:119], v[126:127], v[128:129] op_sel_hi:[1,0]
	v_cvt_pk_bf16_f32 v96, v96, v97
	v_cvt_pk_bf16_f32 v97, v98, v99
	v_pk_mul_f32 v[98:99], v[108:109], v[128:129] op_sel_hi:[1,0]
	v_pk_mul_f32 v[100:101], v[110:111], v[128:129] op_sel_hi:[1,0]
	v_cvt_pk_bf16_f32 v80, v80, v81
	v_cvt_pk_bf16_f32 v81, v82, v83
	v_pk_mul_f32 v[82:83], v[92:93], v[128:129] op_sel_hi:[1,0]
	v_pk_mul_f32 v[84:85], v[94:95], v[128:129] op_sel_hi:[1,0]
	v_cvt_pk_bf16_f32 v116, v116, v117
	v_cvt_pk_bf16_f32 v117, v118, v119
	v_cvt_pk_bf16_f32 v98, v98, v99
	v_cvt_pk_bf16_f32 v99, v100, v101
	v_cvt_pk_bf16_f32 v82, v82, v83
	v_cvt_pk_bf16_f32 v83, v84, v85
	s_mov_b32 s2, 0
	ds_write2_b64 v112, v[114:115], v[116:117] offset0:4 offset1:6
	ds_write2_b64 v112, v[96:97], v[98:99] offset0:12 offset1:14
	ds_write2_b64 v112, v[80:81], v[82:83] offset0:20 offset1:22
	s_waitcnt vmcnt(0)
; template <int NTW>
; DI void inproj_tile(const Params& p, int l, int mt, int ntile, char* lds) {
;     ...
; #pragma unroll
;   for (int im = 0; im < 2; ++im) {
;     const int tl = wm * 64 + im * 32 + l31;
;     const float r = rn[(size_t)mt * 128 + tl];
; #pragma unroll
;     for (int in = 0; in < NTW; ++in)
; #pragma unroll
;       for (int g = 0; g < 4; ++g) {
;         const int n = wn * 32 * NTW + in * 32 + 8 * g + 4 * hi;
;         u32x2 o; o[0] = pk2(acc[in][im][4 * g] * r, acc[in][im][4 * g + 1] * r); o[1] = pk2(acc[in][im][4 * g + 2] * r, acc[in][im][4 * g + 3] * r);
;         *(u32x2*)(lds + tl * RS + n * 2) = o;
;       }
;   }
;   __syncthreads();
	v_pk_mul_f32 v[48:49], v[48:49], v[64:65] op_sel_hi:[1,0]
	v_pk_mul_f32 v[50:51], v[50:51], v[64:65] op_sel_hi:[1,0]
	v_pk_mul_f32 v[32:33], v[32:33], v[64:65] op_sel_hi:[1,0]
	v_pk_mul_f32 v[34:35], v[34:35], v[64:65] op_sel_hi:[1,0]
	v_pk_mul_f32 v[16:17], v[16:17], v[64:65] op_sel_hi:[1,0]
	v_pk_mul_f32 v[18:19], v[18:19], v[64:65] op_sel_hi:[1,0]
	v_pk_mul_f32 v[0:1], v[0:1], v[64:65] op_sel_hi:[1,0]
	v_pk_mul_f32 v[2:3], v[2:3], v[64:65] op_sel_hi:[1,0]
	v_cvt_pk_bf16_f32 v48, v48, v49
	v_cvt_pk_bf16_f32 v49, v50, v51
	v_pk_mul_f32 v[50:51], v[52:53], v[64:65] op_sel_hi:[1,0]
	v_pk_mul_f32 v[52:53], v[54:55], v[64:65] op_sel_hi:[1,0]
	v_cvt_pk_bf16_f32 v32, v32, v33
	v_cvt_pk_bf16_f32 v33, v34, v35
	v_pk_mul_f32 v[34:35], v[36:37], v[64:65] op_sel_hi:[1,0]
	v_pk_mul_f32 v[36:37], v[38:39], v[64:65] op_sel_hi:[1,0]
	v_cvt_pk_bf16_f32 v16, v16, v17
	v_cvt_pk_bf16_f32 v17, v18, v19
	v_pk_mul_f32 v[18:19], v[20:21], v[64:65] op_sel_hi:[1,0]
	v_pk_mul_f32 v[20:21], v[22:23], v[64:65] op_sel_hi:[1,0]
	v_cvt_pk_bf16_f32 v0, v0, v1
	v_cvt_pk_bf16_f32 v1, v2, v3
	v_pk_mul_f32 v[2:3], v[4:5], v[64:65] op_sel_hi:[1,0]
	v_pk_mul_f32 v[4:5], v[6:7], v[64:65] op_sel_hi:[1,0]
	v_cvt_pk_bf16_f32 v50, v50, v51
	v_cvt_pk_bf16_f32 v51, v52, v53
	v_add_u32_e32 v54, 0x4000, v112
	v_cvt_pk_bf16_f32 v34, v34, v35
	v_cvt_pk_bf16_f32 v35, v36, v37
	v_cvt_pk_bf16_f32 v18, v18, v19
	v_cvt_pk_bf16_f32 v19, v20, v21
	v_cvt_pk_bf16_f32 v2, v2, v3
	v_cvt_pk_bf16_f32 v3, v4, v5
	ds_write2_b64 v54, v[48:49], v[50:51] offset0:64 offset1:66
	v_pk_mul_f32 v[48:49], v[56:57], v[64:65] op_sel_hi:[1,0]
	v_pk_mul_f32 v[50:51], v[58:59], v[64:65] op_sel_hi:[1,0]
	ds_write2_b64 v54, v[32:33], v[34:35] offset0:72 offset1:74
	v_pk_mul_f32 v[32:33], v[40:41], v[64:65] op_sel_hi:[1,0]
	v_pk_mul_f32 v[34:35], v[42:43], v[64:65] op_sel_hi:[1,0]
	ds_write2_b64 v54, v[16:17], v[18:19] offset0:80 offset1:82
	v_pk_mul_f32 v[16:17], v[24:25], v[64:65] op_sel_hi:[1,0]
	v_pk_mul_f32 v[18:19], v[26:27], v[64:65] op_sel_hi:[1,0]
	ds_write2_b64 v54, v[0:1], v[2:3] offset0:88 offset1:90
	v_pk_mul_f32 v[0:1], v[8:9], v[64:65] op_sel_hi:[1,0]
	v_pk_mul_f32 v[2:3], v[10:11], v[64:65] op_sel_hi:[1,0]
	v_cvt_pk_bf16_f32 v48, v48, v49
	v_cvt_pk_bf16_f32 v49, v50, v51
	v_pk_mul_f32 v[50:51], v[60:61], v[64:65] op_sel_hi:[1,0]
	v_pk_mul_f32 v[52:53], v[62:63], v[64:65] op_sel_hi:[1,0]
	v_cvt_pk_bf16_f32 v32, v32, v33
	v_cvt_pk_bf16_f32 v33, v34, v35
	v_pk_mul_f32 v[34:35], v[44:45], v[64:65] op_sel_hi:[1,0]
	v_pk_mul_f32 v[36:37], v[46:47], v[64:65] op_sel_hi:[1,0]
	v_cvt_pk_bf16_f32 v16, v16, v17
	v_cvt_pk_bf16_f32 v17, v18, v19
	v_pk_mul_f32 v[18:19], v[28:29], v[64:65] op_sel_hi:[1,0]
	v_pk_mul_f32 v[20:21], v[30:31], v[64:65] op_sel_hi:[1,0]
	v_cvt_pk_bf16_f32 v0, v0, v1
	v_cvt_pk_bf16_f32 v1, v2, v3
	v_pk_mul_f32 v[2:3], v[12:13], v[64:65] op_sel_hi:[1,0]
	v_pk_mul_f32 v[4:5], v[14:15], v[64:65] op_sel_hi:[1,0]
	v_cvt_pk_bf16_f32 v50, v50, v51
	v_cvt_pk_bf16_f32 v51, v52, v53
	v_cvt_pk_bf16_f32 v34, v34, v35
	v_cvt_pk_bf16_f32 v35, v36, v37
	v_cvt_pk_bf16_f32 v18, v18, v19
	v_cvt_pk_bf16_f32 v19, v20, v21
	v_cvt_pk_bf16_f32 v2, v2, v3
	v_cvt_pk_bf16_f32 v3, v4, v5
	ds_write2_b64 v54, v[48:49], v[50:51] offset0:68 offset1:70
	ds_write2_b64 v54, v[32:33], v[34:35] offset0:76 offset1:78
	ds_write2_b64 v54, v[16:17], v[18:19] offset0:84 offset1:86
	ds_write2_b64 v54, v[0:1], v[2:3] offset0:92 offset1:94
	s_waitcnt lgkmcnt(0)
	s_barrier
